# partial-round rebalancing: in-proj last round (96 tiles) and gu ctx third round (384 tiles) spread evenly over all 8 XCDs instead of filling XCDs 0-1 / 0-5
# speedup vs baseline: 1.0007x; 1.0007x over previous
; #define MFMA(a, b, c) __builtin_amdgcn_mfma_f32_32x32x16_bf16((a), (b), (c), 0, 0, 0)
; template <int AI, int BI>
; DI void gemm_tile(const u16* __restrict__ A, int lda, const u16* __restrict__ B, int ldb, int nk, bool swap,
;                   f32x16 (&acc)[AI][BI], char* lds) {
;     ...
;   for (int kt = 0; kt < nk; ++kt) {
;     const char* cur = lds + (kt & 1) * 32768;
;     if (kt + 1 < nk) gemm_stage<AI, BI>(A + (kt + 1) * 64, lda, B + (kt + 1) * 64, ldb, lds + ((kt + 1) & 1) * 32768, tid);
; #pragma unroll
;     for (int ks = 0; ks < 4; ++ks) {
;       const int co = ((ks * 2 + h) ^ sw) << 4;
;       s16x8 fa[AI], fb[BI];
; #pragma unroll
;       for (int i = 0; i < AI; ++i) fa[i] = *(const s16x8*)(cur + offA + i * 4096 + co);
; #pragma unroll
;       for (int i = 0; i < BI; ++i) fb[i] = *(const s16x8*)(cur + offB + i * 4096 + co);
; #pragma unroll
;       for (int i = 0; i < AI; ++i)
; #pragma unroll
;         for (int j = 0; j < BI; ++j) acc[i][j] = MFMA(fa[i], fb[j], acc[i][j]);
;     }
;     asm volatile("s_waitcnt vmcnt(0)" ::: "memory");
;     __syncthreads();
.Lgc1_kloop:
	s_waitcnt vmcnt(6)
	s_barrier
	s_add_u32 m0, s17, 65664
	s_nop 0
	global_load_lds_dwordx4 v90, s[8:9]
	s_add_u32 m0, s17, 69760
	s_nop 0
	global_load_lds_dwordx4 v91, s[8:9]
	s_add_u32 m0, s17, 32768
	s_nop 0
	global_load_lds_dwordx4 v90, s[28:29]
	s_add_u32 m0, s17, 36864
	s_nop 0
	global_load_lds_dwordx4 v91, s[28:29]
	s_add_u32 m0, s17, 40960
	s_nop 0
	global_load_lds_dwordx4 v92, s[28:29]
	s_add_u32 m0, s17, 45056
	s_nop 0
	global_load_lds_dwordx4 v93, s[28:29]
	s_add_u32 s8, s8, 0x80
	s_addc_u32 s9, s9, 0
	s_add_u32 s28, s28, 0x80
	s_addc_u32 s29, s29, 0
	ds_read_b128 v[34:37], v82 offset:0
	ds_read_b128 v[38:41], v86 offset:0
	ds_read_b128 v[42:45], v86 offset:4096
	ds_read_b128 v[46:49], v83 offset:0
	ds_read_b128 v[50:53], v87 offset:0
	ds_read_b128 v[54:57], v87 offset:4096
	ds_read_b128 v[58:61], v84 offset:0
	ds_read_b128 v[62:65], v88 offset:0
	ds_read_b128 v[66:69], v88 offset:4096
	ds_read_b128 v[70:73], v85 offset:0
	ds_read_b128 v[74:77], v89 offset:0
	ds_read_b128 v[78:81], v89 offset:4096
	s_waitcnt lgkmcnt(10)
	v_mfma_f32_32x32x16_bf16 v[2:17], v[34:37], v[38:41], v[2:17]
	s_waitcnt lgkmcnt(9)
	v_mfma_f32_32x32x16_bf16 v[18:33], v[34:37], v[42:45], v[18:33]
	s_waitcnt lgkmcnt(7)
	v_mfma_f32_32x32x16_bf16 v[2:17], v[46:49], v[50:53], v[2:17]
	s_waitcnt lgkmcnt(6)
	v_mfma_f32_32x32x16_bf16 v[18:33], v[46:49], v[54:57], v[18:33]
	s_waitcnt lgkmcnt(4)
	v_mfma_f32_32x32x16_bf16 v[2:17], v[58:61], v[62:65], v[2:17]
	s_waitcnt lgkmcnt(3)
	v_mfma_f32_32x32x16_bf16 v[18:33], v[58:61], v[66:69], v[18:33]
	s_waitcnt lgkmcnt(1)
	v_mfma_f32_32x32x16_bf16 v[2:17], v[70:73], v[74:77], v[2:17]
	s_waitcnt lgkmcnt(0)
	v_mfma_f32_32x32x16_bf16 v[18:33], v[70:73], v[78:81], v[18:33]
	s_waitcnt vmcnt(6)
	s_barrier
	s_add_u32 m0, s17, 49152
	s_nop 0
	global_load_lds_dwordx4 v90, s[8:9]
	s_add_u32 m0, s17, 53248
	s_nop 0
	global_load_lds_dwordx4 v91, s[8:9]
	s_add_u32 m0, s17, 0
	s_nop 0
	global_load_lds_dwordx4 v90, s[28:29]
	s_add_u32 m0, s17, 4096
	s_nop 0
	global_load_lds_dwordx4 v91, s[28:29]
	s_add_u32 m0, s17, 8192
	s_nop 0
	global_load_lds_dwordx4 v92, s[28:29]
	s_add_u32 m0, s17, 12288
	s_nop 0
	global_load_lds_dwordx4 v93, s[28:29]
	s_add_u32 s8, s8, 0x80
	s_addc_u32 s9, s9, 0
	s_add_u32 s28, s28, 0x80
	s_addc_u32 s29, s29, 0
	ds_read_b128 v[34:37], v82 offset:8192
	ds_read_b128 v[38:41], v86 offset:16384
	ds_read_b128 v[42:45], v86 offset:20480
	ds_read_b128 v[46:49], v83 offset:8192
	ds_read_b128 v[50:53], v87 offset:16384
	ds_read_b128 v[54:57], v87 offset:20480
	ds_read_b128 v[58:61], v84 offset:8192
	ds_read_b128 v[62:65], v88 offset:16384
	ds_read_b128 v[66:69], v88 offset:20480
	ds_read_b128 v[70:73], v85 offset:8192
	ds_read_b128 v[74:77], v89 offset:16384
	ds_read_b128 v[78:81], v89 offset:20480
	s_waitcnt lgkmcnt(10)
	v_mfma_f32_32x32x16_bf16 v[2:17], v[34:37], v[38:41], v[2:17]
	s_waitcnt lgkmcnt(9)
	v_mfma_f32_32x32x16_bf16 v[18:33], v[34:37], v[42:45], v[18:33]
	s_waitcnt lgkmcnt(7)
	v_mfma_f32_32x32x16_bf16 v[2:17], v[46:49], v[50:53], v[2:17]
	s_waitcnt lgkmcnt(6)
	v_mfma_f32_32x32x16_bf16 v[18:33], v[46:49], v[54:57], v[18:33]
	s_waitcnt lgkmcnt(4)
	v_mfma_f32_32x32x16_bf16 v[2:17], v[58:61], v[62:65], v[2:17]
	s_waitcnt lgkmcnt(3)
	v_mfma_f32_32x32x16_bf16 v[18:33], v[58:61], v[66:69], v[18:33]
	s_waitcnt lgkmcnt(1)
	v_mfma_f32_32x32x16_bf16 v[2:17], v[70:73], v[74:77], v[2:17]
	s_waitcnt lgkmcnt(0)
	v_mfma_f32_32x32x16_bf16 v[18:33], v[70:73], v[78:81], v[18:33]
	s_waitcnt vmcnt(6)
	s_barrier
	s_add_u32 m0, s17, 57344
	s_nop 0
	global_load_lds_dwordx4 v90, s[8:9]
	s_add_u32 m0, s17, 61440
	s_nop 0
	global_load_lds_dwordx4 v91, s[8:9]
	s_add_u32 m0, s17, 16384
	s_nop 0
	global_load_lds_dwordx4 v90, s[28:29]
	s_add_u32 m0, s17, 20480
	s_nop 0
	global_load_lds_dwordx4 v91, s[28:29]
	s_add_u32 m0, s17, 24576
	s_nop 0
	global_load_lds_dwordx4 v92, s[28:29]
	s_add_u32 m0, s17, 28672
	s_nop 0
	global_load_lds_dwordx4 v93, s[28:29]
	s_add_u32 s8, s8, 0x80
	s_addc_u32 s9, s9, 0
	s_add_u32 s28, s28, 0x80
	s_addc_u32 s29, s29, 0
	ds_read_b128 v[34:37], v82 offset:16512
	ds_read_b128 v[38:41], v86 offset:32768
	ds_read_b128 v[42:45], v86 offset:36864
	ds_read_b128 v[46:49], v83 offset:16512
	ds_read_b128 v[50:53], v87 offset:32768
	ds_read_b128 v[54:57], v87 offset:36864
	ds_read_b128 v[58:61], v84 offset:16512
	ds_read_b128 v[62:65], v88 offset:32768
	ds_read_b128 v[66:69], v88 offset:36864
	ds_read_b128 v[70:73], v85 offset:16512
	ds_read_b128 v[74:77], v89 offset:32768
	ds_read_b128 v[78:81], v89 offset:36864
	s_waitcnt lgkmcnt(10)
	v_mfma_f32_32x32x16_bf16 v[2:17], v[34:37], v[38:41], v[2:17]
	s_waitcnt lgkmcnt(9)
	v_mfma_f32_32x32x16_bf16 v[18:33], v[34:37], v[42:45], v[18:33]
	s_waitcnt lgkmcnt(7)
	v_mfma_f32_32x32x16_bf16 v[2:17], v[46:49], v[50:53], v[2:17]
	s_waitcnt lgkmcnt(6)
	v_mfma_f32_32x32x16_bf16 v[18:33], v[46:49], v[54:57], v[18:33]
	s_waitcnt lgkmcnt(4)
	v_mfma_f32_32x32x16_bf16 v[2:17], v[58:61], v[62:65], v[2:17]
	s_waitcnt lgkmcnt(3)
	v_mfma_f32_32x32x16_bf16 v[18:33], v[58:61], v[66:69], v[18:33]
	s_waitcnt lgkmcnt(1)
	v_mfma_f32_32x32x16_bf16 v[2:17], v[70:73], v[74:77], v[2:17]
	s_waitcnt lgkmcnt(0)
	v_mfma_f32_32x32x16_bf16 v[18:33], v[70:73], v[78:81], v[18:33]
	s_sub_u32 s18, s18, 1
	s_cmp_lg_u32 s18, 0
	s_cbranch_scc1 .Lgc1_kloop
	s_waitcnt vmcnt(6)
	s_barrier
; #define MFMA(a, b, c) __builtin_amdgcn_mfma_f32_32x32x16_bf16((a), (b), (c), 0, 0, 0)
; template <int AI, int BI>
; DI void gemm_tile(const u16* __restrict__ A, int lda, const u16* __restrict__ B, int ldb, int nk, bool swap,
;                   f32x16 (&acc)[AI][BI], char* lds) {
;     ...
;   for (int kt = 0; kt < nk; ++kt) {
;     const char* cur = lds + (kt & 1) * 32768;
;     if (kt + 1 < nk) gemm_stage<AI, BI>(A + (kt + 1) * 64, lda, B + (kt + 1) * 64, ldb, lds + ((kt + 1) & 1) * 32768, tid);
; #pragma unroll
;     for (int ks = 0; ks < 4; ++ks) {
;       const int co = ((ks * 2 + h) ^ sw) << 4;
;       s16x8 fa[AI], fb[BI];
; #pragma unroll
;       for (int i = 0; i < AI; ++i) fa[i] = *(const s16x8*)(cur + offA + i * 4096 + co);
; #pragma unroll
;       for (int i = 0; i < BI; ++i) fb[i] = *(const s16x8*)(cur + offB + i * 4096 + co);
; #pragma unroll
;       for (int i = 0; i < AI; ++i)
; #pragma unroll
;         for (int j = 0; j < BI; ++j) acc[i][j] = MFMA(fa[i], fb[j], acc[i][j]);
;     }
;     asm volatile("s_waitcnt vmcnt(0)" ::: "memory");
;     __syncthreads();
; DI bool next_tile(int rnd, int MT, int NT, int& mt, int& nt) {
;   const int G8 = gridDim.x >> 3, x = blockIdx.x & 7, slot = blockIdx.x >> 3;
;   const int T = (rnd * 8 + x) * G8 + slot;
;   if (T >= MT * NT) return false;
;   const int band = T / (NT * 8), rem = T - band * NT * 8;
;   nt = rem >> 3; mt = band * 8 + (rem & 7);
;   return true;
; }
	s_add_u32 m0, s17, 65664
	s_nop 0
	global_load_lds_dwordx4 v90, s[8:9]
	s_add_u32 m0, s17, 69760
	s_nop 0
	global_load_lds_dwordx4 v91, s[8:9]
	s_add_u32 m0, s17, 32768
	s_nop 0
	global_load_lds_dwordx4 v90, s[28:29]
	s_add_u32 m0, s17, 36864
	s_nop 0
	global_load_lds_dwordx4 v91, s[28:29]
	s_add_u32 m0, s17, 40960
	s_nop 0
	global_load_lds_dwordx4 v92, s[28:29]
	s_add_u32 m0, s17, 45056
	s_nop 0
	global_load_lds_dwordx4 v93, s[28:29]
	s_add_u32 s8, s8, 0x80
	s_addc_u32 s9, s9, 0
	s_add_u32 s28, s28, 0x80
	s_addc_u32 s29, s29, 0
	ds_read_b128 v[34:37], v82 offset:0
	ds_read_b128 v[38:41], v86 offset:0
	ds_read_b128 v[42:45], v86 offset:4096
	ds_read_b128 v[46:49], v83 offset:0
	ds_read_b128 v[50:53], v87 offset:0
	ds_read_b128 v[54:57], v87 offset:4096
	ds_read_b128 v[58:61], v84 offset:0
	ds_read_b128 v[62:65], v88 offset:0
	ds_read_b128 v[66:69], v88 offset:4096
	ds_read_b128 v[70:73], v85 offset:0
	ds_read_b128 v[74:77], v89 offset:0
	ds_read_b128 v[78:81], v89 offset:4096
	s_waitcnt lgkmcnt(10)
	v_mfma_f32_32x32x16_bf16 v[2:17], v[34:37], v[38:41], v[2:17]
	s_waitcnt lgkmcnt(9)
	v_mfma_f32_32x32x16_bf16 v[18:33], v[34:37], v[42:45], v[18:33]
	s_waitcnt lgkmcnt(7)
	v_mfma_f32_32x32x16_bf16 v[2:17], v[46:49], v[50:53], v[2:17]
	s_waitcnt lgkmcnt(6)
	v_mfma_f32_32x32x16_bf16 v[18:33], v[46:49], v[54:57], v[18:33]
	s_waitcnt lgkmcnt(4)
	v_mfma_f32_32x32x16_bf16 v[2:17], v[58:61], v[62:65], v[2:17]
	s_waitcnt lgkmcnt(3)
	v_mfma_f32_32x32x16_bf16 v[18:33], v[58:61], v[66:69], v[18:33]
	s_waitcnt lgkmcnt(1)
	v_mfma_f32_32x32x16_bf16 v[2:17], v[70:73], v[74:77], v[2:17]
	s_waitcnt lgkmcnt(0)
	v_mfma_f32_32x32x16_bf16 v[18:33], v[70:73], v[78:81], v[18:33]
	s_waitcnt vmcnt(6)
	s_barrier
	s_add_u32 m0, s17, 49152
	s_nop 0
	global_load_lds_dwordx4 v90, s[8:9]
	s_add_u32 m0, s17, 53248
	s_nop 0
	global_load_lds_dwordx4 v91, s[8:9]
	s_add_u32 m0, s17, 0
	s_nop 0
	global_load_lds_dwordx4 v90, s[28:29]
	s_add_u32 m0, s17, 4096
	s_nop 0
	global_load_lds_dwordx4 v91, s[28:29]
	s_add_u32 m0, s17, 8192
	s_nop 0
	global_load_lds_dwordx4 v92, s[28:29]
	s_add_u32 m0, s17, 12288
	s_nop 0
	global_load_lds_dwordx4 v93, s[28:29]
	s_add_u32 s8, s8, 0x80
	s_addc_u32 s9, s9, 0
	s_add_u32 s28, s28, 0x80
	s_addc_u32 s29, s29, 0
	ds_read_b128 v[34:37], v82 offset:8192
	ds_read_b128 v[38:41], v86 offset:16384
	ds_read_b128 v[42:45], v86 offset:20480
	ds_read_b128 v[46:49], v83 offset:8192
	ds_read_b128 v[50:53], v87 offset:16384
	ds_read_b128 v[54:57], v87 offset:20480
	ds_read_b128 v[58:61], v84 offset:8192
	ds_read_b128 v[62:65], v88 offset:16384
	ds_read_b128 v[66:69], v88 offset:20480
	ds_read_b128 v[70:73], v85 offset:8192
	ds_read_b128 v[74:77], v89 offset:16384
	ds_read_b128 v[78:81], v89 offset:20480
	s_waitcnt lgkmcnt(10)
	v_mfma_f32_32x32x16_bf16 v[2:17], v[34:37], v[38:41], v[2:17]
	s_waitcnt lgkmcnt(9)
	v_mfma_f32_32x32x16_bf16 v[18:33], v[34:37], v[42:45], v[18:33]
	s_waitcnt lgkmcnt(7)
	v_mfma_f32_32x32x16_bf16 v[2:17], v[46:49], v[50:53], v[2:17]
	s_waitcnt lgkmcnt(6)
	v_mfma_f32_32x32x16_bf16 v[18:33], v[46:49], v[54:57], v[18:33]
	s_waitcnt lgkmcnt(4)
	v_mfma_f32_32x32x16_bf16 v[2:17], v[58:61], v[62:65], v[2:17]
	s_waitcnt lgkmcnt(3)
	v_mfma_f32_32x32x16_bf16 v[18:33], v[58:61], v[66:69], v[18:33]
	s_waitcnt lgkmcnt(1)
	v_mfma_f32_32x32x16_bf16 v[2:17], v[70:73], v[74:77], v[2:17]
	s_waitcnt lgkmcnt(0)
	v_mfma_f32_32x32x16_bf16 v[18:33], v[70:73], v[78:81], v[18:33]
	s_waitcnt vmcnt(6)
	s_barrier
	ds_read_b128 v[34:37], v82 offset:16512
	ds_read_b128 v[38:41], v86 offset:32768
	ds_read_b128 v[42:45], v86 offset:36864
	ds_read_b128 v[46:49], v83 offset:16512
	ds_read_b128 v[50:53], v87 offset:32768
	ds_read_b128 v[54:57], v87 offset:36864
	ds_read_b128 v[58:61], v84 offset:16512
	ds_read_b128 v[62:65], v88 offset:32768
	ds_read_b128 v[66:69], v88 offset:36864
	ds_read_b128 v[70:73], v85 offset:16512
	ds_read_b128 v[74:77], v89 offset:32768
	ds_read_b128 v[78:81], v89 offset:36864
	s_waitcnt lgkmcnt(10)
	v_mfma_f32_32x32x16_bf16 v[2:17], v[34:37], v[38:41], v[2:17]
	s_waitcnt lgkmcnt(9)
	v_mfma_f32_32x32x16_bf16 v[18:33], v[34:37], v[42:45], v[18:33]
	s_waitcnt lgkmcnt(7)
	v_mfma_f32_32x32x16_bf16 v[2:17], v[46:49], v[50:53], v[2:17]
	s_waitcnt lgkmcnt(6)
	v_mfma_f32_32x32x16_bf16 v[18:33], v[46:49], v[54:57], v[18:33]
	s_waitcnt lgkmcnt(4)
	v_mfma_f32_32x32x16_bf16 v[2:17], v[58:61], v[62:65], v[2:17]
	s_waitcnt lgkmcnt(3)
	v_mfma_f32_32x32x16_bf16 v[18:33], v[58:61], v[66:69], v[18:33]
	s_waitcnt lgkmcnt(1)
	v_mfma_f32_32x32x16_bf16 v[2:17], v[70:73], v[74:77], v[2:17]
	s_waitcnt lgkmcnt(0)
	v_mfma_f32_32x32x16_bf16 v[18:33], v[70:73], v[78:81], v[18:33]
	s_waitcnt vmcnt(0)
	s_barrier
	ds_read_b128 v[34:37], v82 offset:0
	ds_read_b128 v[38:41], v86 offset:0
	ds_read_b128 v[42:45], v86 offset:4096
	ds_read_b128 v[46:49], v83 offset:0
	ds_read_b128 v[50:53], v87 offset:0
	ds_read_b128 v[54:57], v87 offset:4096
	ds_read_b128 v[58:61], v84 offset:0
	ds_read_b128 v[62:65], v88 offset:0
	ds_read_b128 v[66:69], v88 offset:4096
	ds_read_b128 v[70:73], v85 offset:0
	ds_read_b128 v[74:77], v89 offset:0
	ds_read_b128 v[78:81], v89 offset:4096
	s_waitcnt lgkmcnt(10)
	v_mfma_f32_32x32x16_bf16 v[2:17], v[34:37], v[38:41], v[2:17]
	s_waitcnt lgkmcnt(9)
	v_mfma_f32_32x32x16_bf16 v[18:33], v[34:37], v[42:45], v[18:33]
	s_waitcnt lgkmcnt(7)
	v_mfma_f32_32x32x16_bf16 v[2:17], v[46:49], v[50:53], v[2:17]
	s_waitcnt lgkmcnt(6)
	v_mfma_f32_32x32x16_bf16 v[18:33], v[46:49], v[54:57], v[18:33]
	s_waitcnt lgkmcnt(4)
	v_mfma_f32_32x32x16_bf16 v[2:17], v[58:61], v[62:65], v[2:17]
	s_waitcnt lgkmcnt(3)
	v_mfma_f32_32x32x16_bf16 v[18:33], v[58:61], v[66:69], v[18:33]
	s_waitcnt lgkmcnt(1)
	v_mfma_f32_32x32x16_bf16 v[2:17], v[70:73], v[74:77], v[2:17]
	s_waitcnt lgkmcnt(0)
	v_mfma_f32_32x32x16_bf16 v[18:33], v[70:73], v[78:81], v[18:33]
	s_add_u32 s36, s36, 0x200
	s_cmpk_lt_u32 s36, 0x400
	s_cbranch_scc1 .Lgc1_keep
	s_cmpk_ge_u32 s36, 0x600
	s_cbranch_scc1 .Lgc1_keep
	s_and_b32 s37, s14, 63
	s_lshr_b32 s40, s14, 6
	s_mul_i32 s40, s40, 48
	s_add_u32 s40, s40, s37
	s_add_u32 s40, s40, 0x400
	s_cmp_lt_u32 s37, 48
	s_cselect_b32 s36, s40, 0x600
; template <int AI, int BI>
; DI void gemm_stage(const u16* __restrict__ A, int lda, const u16* __restrict__ B, int ldb, char* buf, int tid) {
; #pragma unroll
;   for (int i = 0; i < 2 * AI; ++i) {
;     const int S = tid + NTHR * i, row = S >> 3, c = (S & 7) ^ ((row >> 1) & 7);
;     __builtin_amdgcn_global_load_lds((const unsigned*)(A + (size_t)row * lda + c * 8), (__attribute__((address_space(3))) unsigned*)(buf + S * 16), 16, 0, 0);
;   }
; #pragma unroll
;   for (int i = 0; i < 2 * BI; ++i) {
;     const int S = tid + NTHR * i, row = S >> 3, c = (S & 7) ^ ((row >> 1) & 7);
;     __builtin_amdgcn_global_load_lds((const unsigned*)(B + (size_t)row * ldb + c * 8), (__attribute__((address_space(3))) unsigned*)(buf + 16384 + S * 16), 16, 0, 0);
;   }
; }
; DI bool next_tile(int rnd, int MT, int NT, int& mt, int& nt) {
;   const int G8 = gridDim.x >> 3, x = blockIdx.x & 7, slot = blockIdx.x >> 3;
;   const int T = (rnd * 8 + x) * G8 + slot;
;   if (T >= MT * NT) return false;
;   const int band = T / (NT * 8), rem = T - band * NT * 8;
;   nt = rem >> 3; mt = band * 8 + (rem & 7);
;   return true;
; }
.Lgc1_keep:
	s_cmpk_lt_u32 s36, 0x580
	s_cbranch_scc0 .Lgc1_nopf
	s_barrier
	s_mul_i32 s37, s36, 0xba2f
	s_lshr_b32 s37, s37, 24
	s_mul_i32 s40, s37, 0x160
	s_sub_u32 s40, s36, s40
	s_lshr_b32 s41, s40, 3
	s_and_b32 s40, s40, 7
	s_lshl_b32 s37, s37, 3
	s_or_b32 s37, s37, s40
	s_lshl_b32 s37, s37, 6
	s_bitset1_b32 s37, 14
	s_lshl_b32 s46, s37, 11
	s_add_u32 s8, s10, s46
	s_addc_u32 s9, s11, 0
	s_lshl_b32 s46, s41, 18
	s_add_u32 s28, s12, s46
	s_addc_u32 s29, s13, 0
	s_add_u32 m0, s17, 49152
	s_nop 0
	global_load_lds_dwordx4 v90, s[8:9]
	s_add_u32 m0, s17, 53248
	s_nop 0
	global_load_lds_dwordx4 v91, s[8:9]
	s_add_u32 m0, s17, 0
	s_nop 0
	global_load_lds_dwordx4 v90, s[28:29]
	s_add_u32 m0, s17, 4096
	s_nop 0
	global_load_lds_dwordx4 v91, s[28:29]
	s_add_u32 m0, s17, 8192
	s_nop 0
	global_load_lds_dwordx4 v92, s[28:29]
	s_add_u32 m0, s17, 12288
	s_nop 0
	global_load_lds_dwordx4 v93, s[28:29]
	s_add_u32 s8, s8, 0x80
	s_addc_u32 s9, s9, 0
	s_add_u32 s28, s28, 0x80
	s_addc_u32 s29, s29, 0
	s_add_u32 m0, s17, 57344
	s_nop 0
	global_load_lds_dwordx4 v90, s[8:9]
	s_add_u32 m0, s17, 61440
	s_nop 0
	global_load_lds_dwordx4 v91, s[8:9]
	s_add_u32 m0, s17, 16384
	s_nop 0
	global_load_lds_dwordx4 v90, s[28:29]
	s_add_u32 m0, s17, 20480
	s_nop 0
	global_load_lds_dwordx4 v91, s[28:29]
	s_add_u32 m0, s17, 24576
	s_nop 0
	global_load_lds_dwordx4 v92, s[28:29]
	s_add_u32 m0, s17, 28672
	s_nop 0
	global_load_lds_dwordx4 v93, s[28:29]
	s_add_u32 s8, s8, 0x80
	s_addc_u32 s9, s9, 0
	s_add_u32 s28, s28, 0x80
	s_addc_u32 s29, s29, 0

; DI bool next_tile(int rnd, int MT, int NT, int& mt, int& nt) {
;   const int G8 = gridDim.x >> 3, x = blockIdx.x & 7, slot = blockIdx.x >> 3;
;   const int T = (rnd * 8 + x) * G8 + slot;
;   if (T >= MT * NT) return false;
;   const int band = T / (NT * 8), rem = T - band * NT * 8;
;   nt = rem >> 3; mt = band * 8 + (rem & 7);
;   return true;
; }
; DI void phase_in(const Params& p, char* wsb, int layer, char* lds) {
;     ...
;   for (int rnd = 0; next_tile(rnd, 144, 54, mt, nt); ++rnd) {
;     const int m0 = mt * 128, n0 = nt * 128;
;     if (layer == 3 && m0 >= TL && !(n0 == 2048 || n0 == 2176 || (n0 >= 2816 && n0 < 3840))) continue;
.LBB0_586:
	s_lshl_b32 s6, s28, 3
	v_readlane_b32 s7, v244, 8
	s_or_b32 s6, s6, s7
	s_mul_i32 s8, s6, s97
	v_readlane_b32 s6, v243, 14
	s_add_i32 s8, s8, s6
	s_cmpk_lg_u32 s92, 0x200
	s_cbranch_scc1 .Lintail_skip
	s_cmp_lg_u32 s28, 15
	s_cbranch_scc1 .Lintail_skip
	s_mul_i32 s8, s7, 12
	s_add_u32 s8, s8, s6
	s_add_u32 s8, s8, 0x1e00
	s_cmp_lt_u32 s6, 12
	s_cselect_b32 s8, s8, 0x1e60
.Lintail_skip:
	s_cmpk_lt_u32 s8, 0x1e60
	s_cselect_b64 s[6:7], -1, 0
	s_cmpk_gt_u32 s8, 0x1e5f
	s_cbranch_scc1 .LBB0_588
	s_bfe_u32 s9, s8, 0x100004
	s_mulk_i32 s9, 0x12f7
	s_lshr_b32 s9, s9, 17
	s_mul_i32 s10, s9, 0xfffffe50
	s_add_i32 s10, s10, s8
	s_lshl_b32 s9, s9, 3
	s_and_b32 s8, s8, 7
	s_ashr_i32 s61, s10, 3
	s_or_b32 s62, s9, s8
	s_andn2_b64 vcc, exec, s[6:7]
	s_mov_b64 s[6:7], -1
	s_cbranch_vccnz .LBB0_585
	s_branch .LBB0_589
